# LayerNorm loops: 3-buffer ring, two rows of loads in flight per wave behind counted vmcnt (body unrolled x3)
# baseline (speedup 1.0000x reference)
; __device__ __forceinline__ unsigned cvt_pk_bf16(float lo, float hi) { const f32x2c v = {lo, hi}; const bf16x2c b = __builtin_convertvector(v, bf16x2c); return __builtin_bit_cast(unsigned, b); }
; __device__ __forceinline__ float bflo(unsigned u) { return __uint_as_float(u << 16); }
; __device__ __forceinline__ float bfhi(unsigned u) { return __uint_as_float(u & 0xffff0000u); }
; __device__ void phase_ln(KP p, const float* g, const float* b, bool final_out, int tid_in, int r0, int r1, int b0) {
;     ...
;     for (int row = r0 + gw; row < r1; row += nw) {
;         bf16_t* xr = Xb + (size_t)row * 1024 + lane * 8;
;         f32x4 x[4]; float s = 0.f;
; #pragma unroll
;         for (int j = 0; j < 2; ++j) { const u32x4v u = *(const u32x4v*)(xr + 512 * j);
;             x[2 * j] = (f32x4){bflo(u[0]), bfhi(u[0]), bflo(u[1]), bfhi(u[1])}; x[2 * j + 1] = (f32x4){bflo(u[2]), bfhi(u[2]), bflo(u[3]), bfhi(u[3])}; }
; #pragma unroll
;         for (int j = 0; j < 4; ++j) s += x[j][0] + x[j][1] + x[j][2] + x[j][3];
;         const float mu = wave_sum(s, lane) * (1.f / 1024.f); float v = 0.f;
; #pragma unroll
;         for (int j = 0; j < 4; ++j) { x[j] = x[j] - mu; v += x[j][0] * x[j][0] + x[j][1] * x[j][1] + x[j][2] * x[j][2] + x[j][3] * x[j][3]; }
;         const float r = rsqrtf(wave_sum(v, lane) * (1.f / 1024.f) + LN_EPS);
; #pragma unroll
;         for (int j = 0; j < 2; ++j) {
;             const f32x4 y0 = x[2 * j] * r * gv[2 * j] + bv[2 * j], y1 = x[2 * j + 1] * r * gv[2 * j + 1] + bv[2 * j + 1];
;             if (final_out) { float* yo = p->out + (size_t)row * 1024 + lane * 8 + 512 * j; __builtin_nontemporal_store(y0, (f32x4*)yo); __builtin_nontemporal_store(y1, (f32x4*)(yo + 4)); }
;             else { u32x4v o; o[0] = cvt_pk_bf16(y0[0], y0[1]); o[1] = cvt_pk_bf16(y0[2], y0[3]); o[2] = cvt_pk_bf16(y1[0], y1[1]); o[3] = cvt_pk_bf16(y1[2], y1[3]);
;                 *(u32x4v*)(xr + 512 * j) = o; }
;         }
;     }
.LBB0_773:
	v_mov_b32_e32 v94, v36
	v_mov_b32_e32 v95, v37
	global_load_dwordx4 v[70:73], v[94:95], off
	global_load_dwordx4 v[74:77], v[94:95], off offset:1024
	v_lshl_add_u64 v[94:95], v[94:95], 0, s[14:15]
	global_load_dwordx4 v[78:81], v[94:95], off
	global_load_dwordx4 v[82:85], v[94:95], off offset:1024
	v_lshl_add_u64 v[94:95], v[94:95], 0, s[14:15]
	v_mov_b32_e32 v66, 0xba800000
	s_waitcnt vmcnt(2)
.Lln1r_b0:
	v_lshlrev_b32_e32 v48, 16, v70
	v_and_b32_e32 v49, 0xffff0000, v70
	v_lshlrev_b32_e32 v50, 16, v71
	v_and_b32_e32 v51, 0xffff0000, v71
	v_lshlrev_b32_e32 v52, 16, v72
	v_and_b32_e32 v53, 0xffff0000, v72
	v_lshlrev_b32_e32 v54, 16, v73
	v_and_b32_e32 v55, 0xffff0000, v73
	v_lshlrev_b32_e32 v56, 16, v74
	v_and_b32_e32 v57, 0xffff0000, v74
	v_lshlrev_b32_e32 v58, 16, v75
	v_and_b32_e32 v59, 0xffff0000, v75
	v_lshlrev_b32_e32 v60, 16, v76
	v_and_b32_e32 v61, 0xffff0000, v76
	v_lshlrev_b32_e32 v62, 16, v77
	v_and_b32_e32 v63, 0xffff0000, v77
	global_load_dwordx4 v[86:89], v[94:95], off
	global_load_dwordx4 v[90:93], v[94:95], off offset:1024
	v_lshl_add_u64 v[94:95], v[94:95], 0, s[14:15]
	v_pk_add_f32 v[64:65], v[48:49], v[50:51]
	v_pk_add_f32 v[64:65], v[64:65], v[52:53]
	v_pk_add_f32 v[64:65], v[64:65], v[54:55]
	v_pk_add_f32 v[64:65], v[64:65], v[56:57]
	v_pk_add_f32 v[64:65], v[64:65], v[58:59]
	v_pk_add_f32 v[64:65], v[64:65], v[60:61]
	v_pk_add_f32 v[64:65], v[64:65], v[62:63]
	v_add_f32_e32 v35, v64, v65
	s_nop 1
	v_add_f32_dpp v35, v35, v35 quad_perm:[1,0,3,2] row_mask:0xf bank_mask:0xf
	s_nop 1
	v_add_f32_dpp v35, v35, v35 quad_perm:[2,3,0,1] row_mask:0xf bank_mask:0xf
	s_nop 1
	v_add_f32_dpp v35, v35, v35 row_half_mirror row_mask:0xf bank_mask:0xf
	s_nop 1
	v_add_f32_dpp v35, v35, v35 row_mirror row_mask:0xf bank_mask:0xf
	s_nop 1
	v_readlane_b32 vcc_lo, v35, 0
	v_readlane_b32 vcc_hi, v35, 16
	s_nop 1
	v_mov_b32_e32 v8, vcc_lo
	v_add_f32_e32 v8, vcc_hi, v8
	v_readlane_b32 vcc_lo, v35, 32
	v_readlane_b32 vcc_hi, v35, 48
	s_nop 1
	v_add_f32_e32 v8, vcc_lo, v8
	v_add_f32_e32 v35, vcc_hi, v8
	v_mov_b32_e32 v64, v35
	v_pk_fma_f32 v[48:49], v[64:65], v[66:67], v[48:49] op_sel_hi:[0,0,1]
	v_pk_fma_f32 v[50:51], v[64:65], v[66:67], v[50:51] op_sel_hi:[0,0,1]
	v_pk_fma_f32 v[52:53], v[64:65], v[66:67], v[52:53] op_sel_hi:[0,0,1]
	v_pk_fma_f32 v[54:55], v[64:65], v[66:67], v[54:55] op_sel_hi:[0,0,1]
	v_pk_fma_f32 v[56:57], v[64:65], v[66:67], v[56:57] op_sel_hi:[0,0,1]
	v_pk_fma_f32 v[58:59], v[64:65], v[66:67], v[58:59] op_sel_hi:[0,0,1]
	v_pk_fma_f32 v[60:61], v[64:65], v[66:67], v[60:61] op_sel_hi:[0,0,1]
	v_pk_fma_f32 v[62:63], v[64:65], v[66:67], v[62:63] op_sel_hi:[0,0,1]
	v_pk_mul_f32 v[64:65], v[48:49], v[48:49]
	v_pk_fma_f32 v[64:65], v[50:51], v[50:51], v[64:65]
	v_pk_fma_f32 v[64:65], v[52:53], v[52:53], v[64:65]
	v_pk_fma_f32 v[64:65], v[54:55], v[54:55], v[64:65]
	v_pk_fma_f32 v[64:65], v[56:57], v[56:57], v[64:65]
	v_pk_fma_f32 v[64:65], v[58:59], v[58:59], v[64:65]
	v_pk_fma_f32 v[64:65], v[60:61], v[60:61], v[64:65]
	v_pk_fma_f32 v[64:65], v[62:63], v[62:63], v[64:65]
	v_add_f32_e32 v35, v64, v65
	s_nop 1
	v_add_f32_dpp v35, v35, v35 quad_perm:[1,0,3,2] row_mask:0xf bank_mask:0xf
	s_nop 1
	v_add_f32_dpp v35, v35, v35 quad_perm:[2,3,0,1] row_mask:0xf bank_mask:0xf
	s_nop 1
	v_add_f32_dpp v35, v35, v35 row_half_mirror row_mask:0xf bank_mask:0xf
	s_nop 1
	v_add_f32_dpp v35, v35, v35 row_mirror row_mask:0xf bank_mask:0xf
	s_nop 1
	v_readlane_b32 vcc_lo, v35, 0
	v_readlane_b32 vcc_hi, v35, 16
	s_nop 1
	v_mov_b32_e32 v8, vcc_lo
	v_add_f32_e32 v8, vcc_hi, v8
	v_readlane_b32 vcc_lo, v35, 32
	v_readlane_b32 vcc_hi, v35, 48
	s_nop 1
	v_add_f32_e32 v8, vcc_lo, v8
	v_add_f32_e32 v35, vcc_hi, v8
	v_fmamk_f32 v35, v35, 0x3a800000, v248
	v_cmp_gt_f32_e32 vcc, s96, v35
	v_mul_f32_e32 v8, 0x4b800000, v35
	s_nop 0
	v_cndmask_b32_e32 v35, v35, v8, vcc
	v_rsq_f32_e32 v35, v35
	s_nop 0
	v_mul_f32_e32 v8, 0x45800000, v35
	v_cndmask_b32_e32 v64, v35, v8, vcc
	v_pk_mul_f32 v[48:49], v[48:49], v[64:65] op_sel_hi:[1,0]
	v_pk_mul_f32 v[50:51], v[50:51], v[64:65] op_sel_hi:[1,0]
	v_pk_mul_f32 v[52:53], v[52:53], v[64:65] op_sel_hi:[1,0]
	v_pk_mul_f32 v[54:55], v[54:55], v[64:65] op_sel_hi:[1,0]
	v_pk_mul_f32 v[56:57], v[56:57], v[64:65] op_sel_hi:[1,0]
	v_pk_mul_f32 v[58:59], v[58:59], v[64:65] op_sel_hi:[1,0]
	v_pk_mul_f32 v[60:61], v[60:61], v[64:65] op_sel_hi:[1,0]
	v_pk_mul_f32 v[62:63], v[62:63], v[64:65] op_sel_hi:[1,0]
	v_pk_fma_f32 v[48:49], v[4:5], v[48:49], v[14:15]
	v_pk_fma_f32 v[50:51], v[6:7], v[50:51], v[16:17]
	v_pk_fma_f32 v[52:53], v[0:1], v[52:53], v[10:11]
	v_pk_fma_f32 v[54:55], v[2:3], v[54:55], v[12:13]
	v_pk_fma_f32 v[56:57], v[22:23], v[56:57], v[30:31]
	v_pk_fma_f32 v[58:59], v[24:25], v[58:59], v[32:33]
	v_pk_fma_f32 v[60:61], v[18:19], v[60:61], v[26:27]
	v_pk_fma_f32 v[62:63], v[20:21], v[62:63], v[28:29]
	v_cvt_pk_bf16_f32 v48, v48, v49
	v_cvt_pk_bf16_f32 v49, v50, v51
	v_cvt_pk_bf16_f32 v50, v52, v53
	v_cvt_pk_bf16_f32 v51, v54, v55
	v_cvt_pk_bf16_f32 v52, v56, v57
	v_cvt_pk_bf16_f32 v53, v58, v59
	v_cvt_pk_bf16_f32 v54, v60, v61
	v_cvt_pk_bf16_f32 v55, v62, v63
	global_store_dwordx4 v[36:37], v[48:51], off
	global_store_dwordx4 v[36:37], v[52:55], off offset:1024
	v_add_u32_e32 v34, s12, v34
	v_cmp_le_i32_e32 vcc, s0, v34
	v_lshl_add_u64 v[36:37], v[36:37], 0, s[14:15]
	s_or_b64 s[16:17], vcc, s[16:17]
	s_waitcnt vmcnt(4)
	s_andn2_b64 exec, exec, s[16:17]
	s_cbranch_execz .Lln1r_exit
; __device__ __forceinline__ unsigned cvt_pk_bf16(float lo, float hi) { const f32x2c v = {lo, hi}; const bf16x2c b = __builtin_convertvector(v, bf16x2c); return __builtin_bit_cast(unsigned, b); }
; __device__ __forceinline__ float bflo(unsigned u) { return __uint_as_float(u << 16); }
; __device__ __forceinline__ float bfhi(unsigned u) { return __uint_as_float(u & 0xffff0000u); }
; __device__ void phase_ln(KP p, const float* g, const float* b, bool final_out, int tid_in, int r0, int r1, int b0) {
;     ...
;     for (int row = r0 + gw; row < r1; row += nw) {
;         bf16_t* xr = Xb + (size_t)row * 1024 + lane * 8;
;         f32x4 x[4]; float s = 0.f;
; #pragma unroll
;         for (int j = 0; j < 2; ++j) { const u32x4v u = *(const u32x4v*)(xr + 512 * j);
;             x[2 * j] = (f32x4){bflo(u[0]), bfhi(u[0]), bflo(u[1]), bfhi(u[1])}; x[2 * j + 1] = (f32x4){bflo(u[2]), bfhi(u[2]), bflo(u[3]), bfhi(u[3])}; }
; #pragma unroll
;         for (int j = 0; j < 4; ++j) s += x[j][0] + x[j][1] + x[j][2] + x[j][3];
;         const float mu = wave_sum(s, lane) * (1.f / 1024.f); float v = 0.f;
; #pragma unroll
;         for (int j = 0; j < 4; ++j) { x[j] = x[j] - mu; v += x[j][0] * x[j][0] + x[j][1] * x[j][1] + x[j][2] * x[j][2] + x[j][3] * x[j][3]; }
;         const float r = rsqrtf(wave_sum(v, lane) * (1.f / 1024.f) + LN_EPS);
; #pragma unroll
;         for (int j = 0; j < 2; ++j) {
;             const f32x4 y0 = x[2 * j] * r * gv[2 * j] + bv[2 * j], y1 = x[2 * j + 1] * r * gv[2 * j + 1] + bv[2 * j + 1];
;             if (final_out) { float* yo = p->out + (size_t)row * 1024 + lane * 8 + 512 * j; __builtin_nontemporal_store(y0, (f32x4*)yo); __builtin_nontemporal_store(y1, (f32x4*)(yo + 4)); }
;             else { u32x4v o; o[0] = cvt_pk_bf16(y0[0], y0[1]); o[1] = cvt_pk_bf16(y0[2], y0[3]); o[2] = cvt_pk_bf16(y1[0], y1[1]); o[3] = cvt_pk_bf16(y1[2], y1[3]);
;                 *(u32x4v*)(xr + 512 * j) = o; }
;         }
;     }
.Lln1r_b1:
	v_lshlrev_b32_e32 v48, 16, v78
	v_and_b32_e32 v49, 0xffff0000, v78
	v_lshlrev_b32_e32 v50, 16, v79
	v_and_b32_e32 v51, 0xffff0000, v79
	v_lshlrev_b32_e32 v52, 16, v80
	v_and_b32_e32 v53, 0xffff0000, v80
	v_lshlrev_b32_e32 v54, 16, v81
	v_and_b32_e32 v55, 0xffff0000, v81
	v_lshlrev_b32_e32 v56, 16, v82
	v_and_b32_e32 v57, 0xffff0000, v82
	v_lshlrev_b32_e32 v58, 16, v83
	v_and_b32_e32 v59, 0xffff0000, v83
	v_lshlrev_b32_e32 v60, 16, v84
	v_and_b32_e32 v61, 0xffff0000, v84
	v_lshlrev_b32_e32 v62, 16, v85
	v_and_b32_e32 v63, 0xffff0000, v85
	global_load_dwordx4 v[70:73], v[94:95], off
	global_load_dwordx4 v[74:77], v[94:95], off offset:1024
	v_lshl_add_u64 v[94:95], v[94:95], 0, s[14:15]
	v_pk_add_f32 v[64:65], v[48:49], v[50:51]
	v_pk_add_f32 v[64:65], v[64:65], v[52:53]
	v_pk_add_f32 v[64:65], v[64:65], v[54:55]
	v_pk_add_f32 v[64:65], v[64:65], v[56:57]
	v_pk_add_f32 v[64:65], v[64:65], v[58:59]
	v_pk_add_f32 v[64:65], v[64:65], v[60:61]
	v_pk_add_f32 v[64:65], v[64:65], v[62:63]
	v_add_f32_e32 v35, v64, v65
	s_nop 1
	v_add_f32_dpp v35, v35, v35 quad_perm:[1,0,3,2] row_mask:0xf bank_mask:0xf
	s_nop 1
	v_add_f32_dpp v35, v35, v35 quad_perm:[2,3,0,1] row_mask:0xf bank_mask:0xf
	s_nop 1
	v_add_f32_dpp v35, v35, v35 row_half_mirror row_mask:0xf bank_mask:0xf
	s_nop 1
	v_add_f32_dpp v35, v35, v35 row_mirror row_mask:0xf bank_mask:0xf
	s_nop 1
	v_readlane_b32 vcc_lo, v35, 0
	v_readlane_b32 vcc_hi, v35, 16
	s_nop 1
	v_mov_b32_e32 v8, vcc_lo
	v_add_f32_e32 v8, vcc_hi, v8
	v_readlane_b32 vcc_lo, v35, 32
	v_readlane_b32 vcc_hi, v35, 48
	s_nop 1
	v_add_f32_e32 v8, vcc_lo, v8
	v_add_f32_e32 v35, vcc_hi, v8
	v_mov_b32_e32 v64, v35
	v_pk_fma_f32 v[48:49], v[64:65], v[66:67], v[48:49] op_sel_hi:[0,0,1]
	v_pk_fma_f32 v[50:51], v[64:65], v[66:67], v[50:51] op_sel_hi:[0,0,1]
	v_pk_fma_f32 v[52:53], v[64:65], v[66:67], v[52:53] op_sel_hi:[0,0,1]
	v_pk_fma_f32 v[54:55], v[64:65], v[66:67], v[54:55] op_sel_hi:[0,0,1]
	v_pk_fma_f32 v[56:57], v[64:65], v[66:67], v[56:57] op_sel_hi:[0,0,1]
	v_pk_fma_f32 v[58:59], v[64:65], v[66:67], v[58:59] op_sel_hi:[0,0,1]
	v_pk_fma_f32 v[60:61], v[64:65], v[66:67], v[60:61] op_sel_hi:[0,0,1]
	v_pk_fma_f32 v[62:63], v[64:65], v[66:67], v[62:63] op_sel_hi:[0,0,1]
	v_pk_mul_f32 v[64:65], v[48:49], v[48:49]
	v_pk_fma_f32 v[64:65], v[50:51], v[50:51], v[64:65]
	v_pk_fma_f32 v[64:65], v[52:53], v[52:53], v[64:65]
	v_pk_fma_f32 v[64:65], v[54:55], v[54:55], v[64:65]
	v_pk_fma_f32 v[64:65], v[56:57], v[56:57], v[64:65]
	v_pk_fma_f32 v[64:65], v[58:59], v[58:59], v[64:65]
	v_pk_fma_f32 v[64:65], v[60:61], v[60:61], v[64:65]
	v_pk_fma_f32 v[64:65], v[62:63], v[62:63], v[64:65]
	v_add_f32_e32 v35, v64, v65
	s_nop 1
	v_add_f32_dpp v35, v35, v35 quad_perm:[1,0,3,2] row_mask:0xf bank_mask:0xf
	s_nop 1
	v_add_f32_dpp v35, v35, v35 quad_perm:[2,3,0,1] row_mask:0xf bank_mask:0xf
	s_nop 1
	v_add_f32_dpp v35, v35, v35 row_half_mirror row_mask:0xf bank_mask:0xf
	s_nop 1
	v_add_f32_dpp v35, v35, v35 row_mirror row_mask:0xf bank_mask:0xf
	s_nop 1
	v_readlane_b32 vcc_lo, v35, 0
	v_readlane_b32 vcc_hi, v35, 16
	s_nop 1
	v_mov_b32_e32 v8, vcc_lo
	v_add_f32_e32 v8, vcc_hi, v8
	v_readlane_b32 vcc_lo, v35, 32
	v_readlane_b32 vcc_hi, v35, 48
	s_nop 1
	v_add_f32_e32 v8, vcc_lo, v8
	v_add_f32_e32 v35, vcc_hi, v8
	v_fmamk_f32 v35, v35, 0x3a800000, v248
	v_cmp_gt_f32_e32 vcc, s96, v35
	v_mul_f32_e32 v8, 0x4b800000, v35
	s_nop 0
	v_cndmask_b32_e32 v35, v35, v8, vcc
	v_rsq_f32_e32 v35, v35
	s_nop 0
	v_mul_f32_e32 v8, 0x45800000, v35
	v_cndmask_b32_e32 v64, v35, v8, vcc
	v_pk_mul_f32 v[48:49], v[48:49], v[64:65] op_sel_hi:[1,0]
	v_pk_mul_f32 v[50:51], v[50:51], v[64:65] op_sel_hi:[1,0]
	v_pk_mul_f32 v[52:53], v[52:53], v[64:65] op_sel_hi:[1,0]
	v_pk_mul_f32 v[54:55], v[54:55], v[64:65] op_sel_hi:[1,0]
	v_pk_mul_f32 v[56:57], v[56:57], v[64:65] op_sel_hi:[1,0]
	v_pk_mul_f32 v[58:59], v[58:59], v[64:65] op_sel_hi:[1,0]
	v_pk_mul_f32 v[60:61], v[60:61], v[64:65] op_sel_hi:[1,0]
	v_pk_mul_f32 v[62:63], v[62:63], v[64:65] op_sel_hi:[1,0]
	v_pk_fma_f32 v[48:49], v[4:5], v[48:49], v[14:15]
	v_pk_fma_f32 v[50:51], v[6:7], v[50:51], v[16:17]
	v_pk_fma_f32 v[52:53], v[0:1], v[52:53], v[10:11]
	v_pk_fma_f32 v[54:55], v[2:3], v[54:55], v[12:13]
	v_pk_fma_f32 v[56:57], v[22:23], v[56:57], v[30:31]
	v_pk_fma_f32 v[58:59], v[24:25], v[58:59], v[32:33]
	v_pk_fma_f32 v[60:61], v[18:19], v[60:61], v[26:27]
	v_pk_fma_f32 v[62:63], v[20:21], v[62:63], v[28:29]
	v_cvt_pk_bf16_f32 v48, v48, v49
	v_cvt_pk_bf16_f32 v49, v50, v51
	v_cvt_pk_bf16_f32 v50, v52, v53
	v_cvt_pk_bf16_f32 v51, v54, v55
	v_cvt_pk_bf16_f32 v52, v56, v57
	v_cvt_pk_bf16_f32 v53, v58, v59
	v_cvt_pk_bf16_f32 v54, v60, v61
	v_cvt_pk_bf16_f32 v55, v62, v63
	global_store_dwordx4 v[36:37], v[48:51], off
	global_store_dwordx4 v[36:37], v[52:55], off offset:1024
	v_add_u32_e32 v34, s12, v34
	v_cmp_le_i32_e32 vcc, s0, v34
	v_lshl_add_u64 v[36:37], v[36:37], 0, s[14:15]
	s_or_b64 s[16:17], vcc, s[16:17]
	s_waitcnt vmcnt(4)
	s_andn2_b64 exec, exec, s[16:17]
	s_cbranch_execz .Lln1r_exit
; __device__ __forceinline__ unsigned cvt_pk_bf16(float lo, float hi) { const f32x2c v = {lo, hi}; const bf16x2c b = __builtin_convertvector(v, bf16x2c); return __builtin_bit_cast(unsigned, b); }
; __device__ __forceinline__ float bflo(unsigned u) { return __uint_as_float(u << 16); }
; __device__ __forceinline__ float bfhi(unsigned u) { return __uint_as_float(u & 0xffff0000u); }
; __device__ void phase_ln(KP p, const float* g, const float* b, bool final_out, int tid_in, int r0, int r1, int b0) {
;     ...
;     for (int row = r0 + gw; row < r1; row += nw) {
;         bf16_t* xr = Xb + (size_t)row * 1024 + lane * 8;
;         f32x4 x[4]; float s = 0.f;
; #pragma unroll
;         for (int j = 0; j < 2; ++j) { const u32x4v u = *(const u32x4v*)(xr + 512 * j);
;             x[2 * j] = (f32x4){bflo(u[0]), bfhi(u[0]), bflo(u[1]), bfhi(u[1])}; x[2 * j + 1] = (f32x4){bflo(u[2]), bfhi(u[2]), bflo(u[3]), bfhi(u[3])}; }
; #pragma unroll
;         for (int j = 0; j < 4; ++j) s += x[j][0] + x[j][1] + x[j][2] + x[j][3];
;         const float mu = wave_sum(s, lane) * (1.f / 1024.f); float v = 0.f;
; #pragma unroll
;         for (int j = 0; j < 4; ++j) { x[j] = x[j] - mu; v += x[j][0] * x[j][0] + x[j][1] * x[j][1] + x[j][2] * x[j][2] + x[j][3] * x[j][3]; }
;         const float r = rsqrtf(wave_sum(v, lane) * (1.f / 1024.f) + LN_EPS);
; #pragma unroll
;         for (int j = 0; j < 2; ++j) {
;             const f32x4 y0 = x[2 * j] * r * gv[2 * j] + bv[2 * j], y1 = x[2 * j + 1] * r * gv[2 * j + 1] + bv[2 * j + 1];
;             if (final_out) { float* yo = p->out + (size_t)row * 1024 + lane * 8 + 512 * j; __builtin_nontemporal_store(y0, (f32x4*)yo); __builtin_nontemporal_store(y1, (f32x4*)(yo + 4)); }
;             else { u32x4v o; o[0] = cvt_pk_bf16(y0[0], y0[1]); o[1] = cvt_pk_bf16(y0[2], y0[3]); o[2] = cvt_pk_bf16(y1[0], y1[1]); o[3] = cvt_pk_bf16(y1[2], y1[3]);
;                 *(u32x4v*)(xr + 512 * j) = o; }
;         }
;     }
.Lln1r_b2:
	v_lshlrev_b32_e32 v48, 16, v86
	v_and_b32_e32 v49, 0xffff0000, v86
	v_lshlrev_b32_e32 v50, 16, v87
	v_and_b32_e32 v51, 0xffff0000, v87
	v_lshlrev_b32_e32 v52, 16, v88
	v_and_b32_e32 v53, 0xffff0000, v88
	v_lshlrev_b32_e32 v54, 16, v89
	v_and_b32_e32 v55, 0xffff0000, v89
	v_lshlrev_b32_e32 v56, 16, v90
	v_and_b32_e32 v57, 0xffff0000, v90
	v_lshlrev_b32_e32 v58, 16, v91
	v_and_b32_e32 v59, 0xffff0000, v91
	v_lshlrev_b32_e32 v60, 16, v92
	v_and_b32_e32 v61, 0xffff0000, v92
	v_lshlrev_b32_e32 v62, 16, v93
	v_and_b32_e32 v63, 0xffff0000, v93
	global_load_dwordx4 v[78:81], v[94:95], off
	global_load_dwordx4 v[82:85], v[94:95], off offset:1024
	v_lshl_add_u64 v[94:95], v[94:95], 0, s[14:15]
	v_pk_add_f32 v[64:65], v[48:49], v[50:51]
	v_pk_add_f32 v[64:65], v[64:65], v[52:53]
	v_pk_add_f32 v[64:65], v[64:65], v[54:55]
	v_pk_add_f32 v[64:65], v[64:65], v[56:57]
	v_pk_add_f32 v[64:65], v[64:65], v[58:59]
	v_pk_add_f32 v[64:65], v[64:65], v[60:61]
	v_pk_add_f32 v[64:65], v[64:65], v[62:63]
	v_add_f32_e32 v35, v64, v65
	s_nop 1
	v_add_f32_dpp v35, v35, v35 quad_perm:[1,0,3,2] row_mask:0xf bank_mask:0xf
	s_nop 1
	v_add_f32_dpp v35, v35, v35 quad_perm:[2,3,0,1] row_mask:0xf bank_mask:0xf
	s_nop 1
	v_add_f32_dpp v35, v35, v35 row_half_mirror row_mask:0xf bank_mask:0xf
	s_nop 1
	v_add_f32_dpp v35, v35, v35 row_mirror row_mask:0xf bank_mask:0xf
	s_nop 1
	v_readlane_b32 vcc_lo, v35, 0
	v_readlane_b32 vcc_hi, v35, 16
	s_nop 1
	v_mov_b32_e32 v8, vcc_lo
	v_add_f32_e32 v8, vcc_hi, v8
	v_readlane_b32 vcc_lo, v35, 32
	v_readlane_b32 vcc_hi, v35, 48
	s_nop 1
	v_add_f32_e32 v8, vcc_lo, v8
	v_add_f32_e32 v35, vcc_hi, v8
	v_mov_b32_e32 v64, v35
	v_pk_fma_f32 v[48:49], v[64:65], v[66:67], v[48:49] op_sel_hi:[0,0,1]
	v_pk_fma_f32 v[50:51], v[64:65], v[66:67], v[50:51] op_sel_hi:[0,0,1]
	v_pk_fma_f32 v[52:53], v[64:65], v[66:67], v[52:53] op_sel_hi:[0,0,1]
	v_pk_fma_f32 v[54:55], v[64:65], v[66:67], v[54:55] op_sel_hi:[0,0,1]
	v_pk_fma_f32 v[56:57], v[64:65], v[66:67], v[56:57] op_sel_hi:[0,0,1]
	v_pk_fma_f32 v[58:59], v[64:65], v[66:67], v[58:59] op_sel_hi:[0,0,1]
	v_pk_fma_f32 v[60:61], v[64:65], v[66:67], v[60:61] op_sel_hi:[0,0,1]
	v_pk_fma_f32 v[62:63], v[64:65], v[66:67], v[62:63] op_sel_hi:[0,0,1]
	v_pk_mul_f32 v[64:65], v[48:49], v[48:49]
	v_pk_fma_f32 v[64:65], v[50:51], v[50:51], v[64:65]
	v_pk_fma_f32 v[64:65], v[52:53], v[52:53], v[64:65]
	v_pk_fma_f32 v[64:65], v[54:55], v[54:55], v[64:65]
	v_pk_fma_f32 v[64:65], v[56:57], v[56:57], v[64:65]
	v_pk_fma_f32 v[64:65], v[58:59], v[58:59], v[64:65]
	v_pk_fma_f32 v[64:65], v[60:61], v[60:61], v[64:65]
	v_pk_fma_f32 v[64:65], v[62:63], v[62:63], v[64:65]
	v_add_f32_e32 v35, v64, v65
	s_nop 1
	v_add_f32_dpp v35, v35, v35 quad_perm:[1,0,3,2] row_mask:0xf bank_mask:0xf
	s_nop 1
	v_add_f32_dpp v35, v35, v35 quad_perm:[2,3,0,1] row_mask:0xf bank_mask:0xf
	s_nop 1
	v_add_f32_dpp v35, v35, v35 row_half_mirror row_mask:0xf bank_mask:0xf
	s_nop 1
	v_add_f32_dpp v35, v35, v35 row_mirror row_mask:0xf bank_mask:0xf
	s_nop 1
	v_readlane_b32 vcc_lo, v35, 0
	v_readlane_b32 vcc_hi, v35, 16
	s_nop 1
	v_mov_b32_e32 v8, vcc_lo
	v_add_f32_e32 v8, vcc_hi, v8
	v_readlane_b32 vcc_lo, v35, 32
	v_readlane_b32 vcc_hi, v35, 48
	s_nop 1
	v_add_f32_e32 v8, vcc_lo, v8
	v_add_f32_e32 v35, vcc_hi, v8
	v_fmamk_f32 v35, v35, 0x3a800000, v248
	v_cmp_gt_f32_e32 vcc, s96, v35
	v_mul_f32_e32 v8, 0x4b800000, v35
	s_nop 0
	v_cndmask_b32_e32 v35, v35, v8, vcc
	v_rsq_f32_e32 v35, v35
	s_nop 0
	v_mul_f32_e32 v8, 0x45800000, v35
	v_cndmask_b32_e32 v64, v35, v8, vcc
	v_pk_mul_f32 v[48:49], v[48:49], v[64:65] op_sel_hi:[1,0]
	v_pk_mul_f32 v[50:51], v[50:51], v[64:65] op_sel_hi:[1,0]
	v_pk_mul_f32 v[52:53], v[52:53], v[64:65] op_sel_hi:[1,0]
	v_pk_mul_f32 v[54:55], v[54:55], v[64:65] op_sel_hi:[1,0]
	v_pk_mul_f32 v[56:57], v[56:57], v[64:65] op_sel_hi:[1,0]
	v_pk_mul_f32 v[58:59], v[58:59], v[64:65] op_sel_hi:[1,0]
	v_pk_mul_f32 v[60:61], v[60:61], v[64:65] op_sel_hi:[1,0]
	v_pk_mul_f32 v[62:63], v[62:63], v[64:65] op_sel_hi:[1,0]
	v_pk_fma_f32 v[48:49], v[4:5], v[48:49], v[14:15]
	v_pk_fma_f32 v[50:51], v[6:7], v[50:51], v[16:17]
	v_pk_fma_f32 v[52:53], v[0:1], v[52:53], v[10:11]
	v_pk_fma_f32 v[54:55], v[2:3], v[54:55], v[12:13]
	v_pk_fma_f32 v[56:57], v[22:23], v[56:57], v[30:31]
	v_pk_fma_f32 v[58:59], v[24:25], v[58:59], v[32:33]
	v_pk_fma_f32 v[60:61], v[18:19], v[60:61], v[26:27]
	v_pk_fma_f32 v[62:63], v[20:21], v[62:63], v[28:29]
	v_cvt_pk_bf16_f32 v48, v48, v49
	v_cvt_pk_bf16_f32 v49, v50, v51
	v_cvt_pk_bf16_f32 v50, v52, v53
	v_cvt_pk_bf16_f32 v51, v54, v55
	v_cvt_pk_bf16_f32 v52, v56, v57
	v_cvt_pk_bf16_f32 v53, v58, v59
	v_cvt_pk_bf16_f32 v54, v60, v61
	v_cvt_pk_bf16_f32 v55, v62, v63
	global_store_dwordx4 v[36:37], v[48:51], off
	global_store_dwordx4 v[36:37], v[52:55], off offset:1024
	v_add_u32_e32 v34, s12, v34
	v_cmp_le_i32_e32 vcc, s0, v34
	v_lshl_add_u64 v[36:37], v[36:37], 0, s[14:15]
	s_or_b64 s[16:17], vcc, s[16:17]
	s_waitcnt vmcnt(4)
	s_andn2_b64 exec, exec, s[16:17]
	s_cbranch_execnz .Lln1r_b0
.Lln1r_exit:
	s_waitcnt vmcnt(0)
.LBB0_774:
	s_or_b64 exec, exec, s[10:11]

; __device__ __forceinline__ unsigned cvt_pk_bf16(float lo, float hi) { const f32x2c v = {lo, hi}; const bf16x2c b = __builtin_convertvector(v, bf16x2c); return __builtin_bit_cast(unsigned, b); }
; __device__ __forceinline__ float bflo(unsigned u) { return __uint_as_float(u << 16); }
; __device__ __forceinline__ float bfhi(unsigned u) { return __uint_as_float(u & 0xffff0000u); }
; __device__ void phase_ln(KP p, const float* g, const float* b, bool final_out, int tid_in, int r0, int r1, int b0) {
;     ...
;     for (int row = r0 + gw; row < r1; row += nw) {
;         bf16_t* xr = Xb + (size_t)row * 1024 + lane * 8;
;         f32x4 x[4]; float s = 0.f;
; #pragma unroll
;         for (int j = 0; j < 2; ++j) { const u32x4v u = *(const u32x4v*)(xr + 512 * j);
;             x[2 * j] = (f32x4){bflo(u[0]), bfhi(u[0]), bflo(u[1]), bfhi(u[1])}; x[2 * j + 1] = (f32x4){bflo(u[2]), bfhi(u[2]), bflo(u[3]), bfhi(u[3])}; }
; #pragma unroll
;         for (int j = 0; j < 4; ++j) s += x[j][0] + x[j][1] + x[j][2] + x[j][3];
;         const float mu = wave_sum(s, lane) * (1.f / 1024.f); float v = 0.f;
; #pragma unroll
;         for (int j = 0; j < 4; ++j) { x[j] = x[j] - mu; v += x[j][0] * x[j][0] + x[j][1] * x[j][1] + x[j][2] * x[j][2] + x[j][3] * x[j][3]; }
;         const float r = rsqrtf(wave_sum(v, lane) * (1.f / 1024.f) + LN_EPS);
; #pragma unroll
;         for (int j = 0; j < 2; ++j) {
;             const f32x4 y0 = x[2 * j] * r * gv[2 * j] + bv[2 * j], y1 = x[2 * j + 1] * r * gv[2 * j + 1] + bv[2 * j + 1];
;             if (final_out) { float* yo = p->out + (size_t)row * 1024 + lane * 8 + 512 * j; __builtin_nontemporal_store(y0, (f32x4*)yo); __builtin_nontemporal_store(y1, (f32x4*)(yo + 4)); }
;             else { u32x4v o; o[0] = cvt_pk_bf16(y0[0], y0[1]); o[1] = cvt_pk_bf16(y0[2], y0[3]); o[2] = cvt_pk_bf16(y1[0], y1[1]); o[3] = cvt_pk_bf16(y1[2], y1[3]);
;                 *(u32x4v*)(xr + 512 * j) = o; }
.LBB0_989:
	v_mov_b32_e32 v94, v44
	v_mov_b32_e32 v95, v45
	global_load_dwordx4 v[70:73], v[94:95], off offset:-1024
	global_load_dwordx4 v[74:77], v[94:95], off
	v_lshl_add_u64 v[94:95], v[94:95], 0, s[34:35]
	global_load_dwordx4 v[78:81], v[94:95], off offset:-1024
	global_load_dwordx4 v[82:85], v[94:95], off
	v_lshl_add_u64 v[94:95], v[94:95], 0, s[34:35]
	v_mov_b32_e32 v40, 0xba800000
	s_waitcnt vmcnt(2)
.Lln2r_b0:
	v_lshlrev_b32_e32 v52, 16, v70
	v_and_b32_e32 v53, 0xffff0000, v70
	v_lshlrev_b32_e32 v54, 16, v71
	v_and_b32_e32 v55, 0xffff0000, v71
	v_lshlrev_b32_e32 v56, 16, v72
	v_and_b32_e32 v57, 0xffff0000, v72
	v_lshlrev_b32_e32 v58, 16, v73
	v_and_b32_e32 v59, 0xffff0000, v73
	v_lshlrev_b32_e32 v60, 16, v74
	v_and_b32_e32 v61, 0xffff0000, v74
	v_lshlrev_b32_e32 v62, 16, v75
	v_and_b32_e32 v63, 0xffff0000, v75
	v_lshlrev_b32_e32 v64, 16, v76
	v_and_b32_e32 v65, 0xffff0000, v76
	v_lshlrev_b32_e32 v66, 16, v77
	v_and_b32_e32 v67, 0xffff0000, v77
	global_load_dwordx4 v[86:89], v[94:95], off offset:-1024
	global_load_dwordx4 v[90:93], v[94:95], off
	v_lshl_add_u64 v[94:95], v[94:95], 0, s[34:35]
	v_pk_add_f32 v[68:69], v[52:53], v[54:55]
	v_pk_add_f32 v[68:69], v[68:69], v[56:57]
	v_pk_add_f32 v[68:69], v[68:69], v[58:59]
	v_pk_add_f32 v[68:69], v[68:69], v[60:61]
	v_pk_add_f32 v[68:69], v[68:69], v[62:63]
	v_pk_add_f32 v[68:69], v[68:69], v[64:65]
	v_pk_add_f32 v[68:69], v[68:69], v[66:67]
	v_add_f32_e32 v43, v68, v69
	s_nop 1
	v_add_f32_dpp v43, v43, v43 quad_perm:[1,0,3,2] row_mask:0xf bank_mask:0xf
	s_nop 1
	v_add_f32_dpp v43, v43, v43 quad_perm:[2,3,0,1] row_mask:0xf bank_mask:0xf
	s_nop 1
	v_add_f32_dpp v43, v43, v43 row_half_mirror row_mask:0xf bank_mask:0xf
	s_nop 1
	v_add_f32_dpp v43, v43, v43 row_mirror row_mask:0xf bank_mask:0xf
	s_nop 1
	v_readlane_b32 vcc_lo, v43, 0
	v_readlane_b32 vcc_hi, v43, 16
	s_nop 1
	v_mov_b32_e32 v8, vcc_lo
	v_add_f32_e32 v8, vcc_hi, v8
	v_readlane_b32 vcc_lo, v43, 32
	v_readlane_b32 vcc_hi, v43, 48
	s_nop 1
	v_add_f32_e32 v8, vcc_lo, v8
	v_add_f32_e32 v43, vcc_hi, v8
	v_mov_b32_e32 v68, v43
	v_pk_fma_f32 v[52:53], v[68:69], v[40:41], v[52:53] op_sel_hi:[0,0,1]
	v_pk_fma_f32 v[54:55], v[68:69], v[40:41], v[54:55] op_sel_hi:[0,0,1]
	v_pk_fma_f32 v[56:57], v[68:69], v[40:41], v[56:57] op_sel_hi:[0,0,1]
	v_pk_fma_f32 v[58:59], v[68:69], v[40:41], v[58:59] op_sel_hi:[0,0,1]
	v_pk_fma_f32 v[60:61], v[68:69], v[40:41], v[60:61] op_sel_hi:[0,0,1]
	v_pk_fma_f32 v[62:63], v[68:69], v[40:41], v[62:63] op_sel_hi:[0,0,1]
	v_pk_fma_f32 v[64:65], v[68:69], v[40:41], v[64:65] op_sel_hi:[0,0,1]
	v_pk_fma_f32 v[66:67], v[68:69], v[40:41], v[66:67] op_sel_hi:[0,0,1]
	v_pk_mul_f32 v[68:69], v[52:53], v[52:53]
	v_pk_fma_f32 v[68:69], v[54:55], v[54:55], v[68:69]
	v_pk_fma_f32 v[68:69], v[56:57], v[56:57], v[68:69]
	v_pk_fma_f32 v[68:69], v[58:59], v[58:59], v[68:69]
	v_pk_fma_f32 v[68:69], v[60:61], v[60:61], v[68:69]
	v_pk_fma_f32 v[68:69], v[62:63], v[62:63], v[68:69]
	v_pk_fma_f32 v[68:69], v[64:65], v[64:65], v[68:69]
	v_pk_fma_f32 v[68:69], v[66:67], v[66:67], v[68:69]
	v_add_f32_e32 v43, v68, v69
	s_nop 1
	v_add_f32_dpp v43, v43, v43 quad_perm:[1,0,3,2] row_mask:0xf bank_mask:0xf
	s_nop 1
	v_add_f32_dpp v43, v43, v43 quad_perm:[2,3,0,1] row_mask:0xf bank_mask:0xf
	s_nop 1
	v_add_f32_dpp v43, v43, v43 row_half_mirror row_mask:0xf bank_mask:0xf
	s_nop 1
	v_add_f32_dpp v43, v43, v43 row_mirror row_mask:0xf bank_mask:0xf
	s_nop 1
	v_readlane_b32 vcc_lo, v43, 0
	v_readlane_b32 vcc_hi, v43, 16
	s_nop 1
	v_mov_b32_e32 v8, vcc_lo
	v_add_f32_e32 v8, vcc_hi, v8
	v_readlane_b32 vcc_lo, v43, 32
	v_readlane_b32 vcc_hi, v43, 48
	s_nop 1
	v_add_f32_e32 v8, vcc_lo, v8
	v_add_f32_e32 v43, vcc_hi, v8
	v_fmamk_f32 v43, v43, 0x3a800000, v248
	v_cmp_gt_f32_e32 vcc, s96, v43
	v_mul_f32_e32 v8, 0x4b800000, v43
	s_nop 0
	v_cndmask_b32_e32 v43, v43, v8, vcc
	v_rsq_f32_e32 v43, v43
	s_nop 0
	v_mul_f32_e32 v8, 0x45800000, v43
	v_cndmask_b32_e32 v68, v43, v8, vcc
	v_pk_mul_f32 v[52:53], v[52:53], v[68:69] op_sel_hi:[1,0]
	v_pk_mul_f32 v[54:55], v[54:55], v[68:69] op_sel_hi:[1,0]
	v_pk_mul_f32 v[56:57], v[56:57], v[68:69] op_sel_hi:[1,0]
	v_pk_mul_f32 v[58:59], v[58:59], v[68:69] op_sel_hi:[1,0]
	v_pk_mul_f32 v[60:61], v[60:61], v[68:69] op_sel_hi:[1,0]
	v_pk_mul_f32 v[62:63], v[62:63], v[68:69] op_sel_hi:[1,0]
	v_pk_mul_f32 v[64:65], v[64:65], v[68:69] op_sel_hi:[1,0]
	v_pk_mul_f32 v[66:67], v[66:67], v[68:69] op_sel_hi:[1,0]
	v_pk_fma_f32 v[52:53], v[4:5], v[52:53], v[14:15]
	v_pk_fma_f32 v[54:55], v[6:7], v[54:55], v[16:17]
	v_pk_fma_f32 v[56:57], v[0:1], v[56:57], v[10:11]
	v_pk_fma_f32 v[58:59], v[2:3], v[58:59], v[12:13]
	v_pk_fma_f32 v[60:61], v[22:23], v[60:61], v[30:31]
	v_pk_fma_f32 v[62:63], v[24:25], v[62:63], v[32:33]
	v_pk_fma_f32 v[64:65], v[18:19], v[64:65], v[26:27]
	v_pk_fma_f32 v[66:67], v[20:21], v[66:67], v[28:29]
	s_and_b64 vcc, exec, s[6:7]
	s_cbranch_vccz .Lln2r_f32_0
	v_cvt_pk_bf16_f32 v52, v52, v53
	v_cvt_pk_bf16_f32 v53, v54, v55
	v_cvt_pk_bf16_f32 v54, v56, v57
	v_cvt_pk_bf16_f32 v55, v58, v59
	v_cvt_pk_bf16_f32 v56, v60, v61
	v_cvt_pk_bf16_f32 v57, v62, v63
	v_cvt_pk_bf16_f32 v58, v64, v65
	v_cvt_pk_bf16_f32 v59, v66, v67
	global_store_dwordx4 v[44:45], v[52:55], off offset:-1024
	global_store_dwordx4 v[44:45], v[56:59], off
	s_waitcnt vmcnt(4)
	s_branch .Lln2r_latch_0
; __device__ __forceinline__ unsigned cvt_pk_bf16(float lo, float hi) { const f32x2c v = {lo, hi}; const bf16x2c b = __builtin_convertvector(v, bf16x2c); return __builtin_bit_cast(unsigned, b); }
; __device__ __forceinline__ float bflo(unsigned u) { return __uint_as_float(u << 16); }
; __device__ __forceinline__ float bfhi(unsigned u) { return __uint_as_float(u & 0xffff0000u); }
; __device__ void phase_ln(KP p, const float* g, const float* b, bool final_out, int tid_in, int r0, int r1, int b0) {
;     ...
;     for (int row = r0 + gw; row < r1; row += nw) {
;         bf16_t* xr = Xb + (size_t)row * 1024 + lane * 8;
;         f32x4 x[4]; float s = 0.f;
; #pragma unroll
;         for (int j = 0; j < 2; ++j) { const u32x4v u = *(const u32x4v*)(xr + 512 * j);
;             x[2 * j] = (f32x4){bflo(u[0]), bfhi(u[0]), bflo(u[1]), bfhi(u[1])}; x[2 * j + 1] = (f32x4){bflo(u[2]), bfhi(u[2]), bflo(u[3]), bfhi(u[3])}; }
; #pragma unroll
;         for (int j = 0; j < 4; ++j) s += x[j][0] + x[j][1] + x[j][2] + x[j][3];
;         const float mu = wave_sum(s, lane) * (1.f / 1024.f); float v = 0.f;
; #pragma unroll
;         for (int j = 0; j < 4; ++j) { x[j] = x[j] - mu; v += x[j][0] * x[j][0] + x[j][1] * x[j][1] + x[j][2] * x[j][2] + x[j][3] * x[j][3]; }
;         const float r = rsqrtf(wave_sum(v, lane) * (1.f / 1024.f) + LN_EPS);
; #pragma unroll
;         for (int j = 0; j < 2; ++j) {
;             const f32x4 y0 = x[2 * j] * r * gv[2 * j] + bv[2 * j], y1 = x[2 * j + 1] * r * gv[2 * j + 1] + bv[2 * j + 1];
;             if (final_out) { float* yo = p->out + (size_t)row * 1024 + lane * 8 + 512 * j; __builtin_nontemporal_store(y0, (f32x4*)yo); __builtin_nontemporal_store(y1, (f32x4*)(yo + 4)); }
;             else { u32x4v o; o[0] = cvt_pk_bf16(y0[0], y0[1]); o[1] = cvt_pk_bf16(y0[2], y0[3]); o[2] = cvt_pk_bf16(y1[0], y1[1]); o[3] = cvt_pk_bf16(y1[2], y1[3]);
;                 *(u32x4v*)(xr + 512 * j) = o; }
;         }
;     }
.Lln2r_f32_0:
	global_store_dwordx4 v[46:47], v[52:55], off offset:-2064 nt
	global_store_dwordx4 v[46:47], v[56:59], off offset:-2048 nt
	global_store_dwordx4 v[46:47], v[60:63], off offset:-16 nt
	global_store_dwordx4 v[46:47], v[64:67], off nt
	s_waitcnt vmcnt(6)
.Lln2r_latch_0:
	v_add_u32_e32 v42, s30, v42
	v_cmp_le_i32_e32 vcc, s0, v42
	v_lshl_add_u64 v[44:45], v[44:45], 0, s[34:35]
	s_or_b64 s[48:49], vcc, s[48:49]
	v_lshl_add_u64 v[46:47], v[46:47], 0, s[42:43]
	s_andn2_b64 exec, exec, s[48:49]
	s_cbranch_execz .Lln2r_exit
.Lln2r_b1:
	v_lshlrev_b32_e32 v52, 16, v78
	v_and_b32_e32 v53, 0xffff0000, v78
	v_lshlrev_b32_e32 v54, 16, v79
	v_and_b32_e32 v55, 0xffff0000, v79
	v_lshlrev_b32_e32 v56, 16, v80
	v_and_b32_e32 v57, 0xffff0000, v80
	v_lshlrev_b32_e32 v58, 16, v81
	v_and_b32_e32 v59, 0xffff0000, v81
	v_lshlrev_b32_e32 v60, 16, v82
	v_and_b32_e32 v61, 0xffff0000, v82
	v_lshlrev_b32_e32 v62, 16, v83
	v_and_b32_e32 v63, 0xffff0000, v83
	v_lshlrev_b32_e32 v64, 16, v84
	v_and_b32_e32 v65, 0xffff0000, v84
	v_lshlrev_b32_e32 v66, 16, v85
	v_and_b32_e32 v67, 0xffff0000, v85
	global_load_dwordx4 v[70:73], v[94:95], off offset:-1024
	global_load_dwordx4 v[74:77], v[94:95], off
	v_lshl_add_u64 v[94:95], v[94:95], 0, s[34:35]
	v_pk_add_f32 v[68:69], v[52:53], v[54:55]
	v_pk_add_f32 v[68:69], v[68:69], v[56:57]
	v_pk_add_f32 v[68:69], v[68:69], v[58:59]
	v_pk_add_f32 v[68:69], v[68:69], v[60:61]
	v_pk_add_f32 v[68:69], v[68:69], v[62:63]
	v_pk_add_f32 v[68:69], v[68:69], v[64:65]
	v_pk_add_f32 v[68:69], v[68:69], v[66:67]
	v_add_f32_e32 v43, v68, v69
	s_nop 1
	v_add_f32_dpp v43, v43, v43 quad_perm:[1,0,3,2] row_mask:0xf bank_mask:0xf
	s_nop 1
	v_add_f32_dpp v43, v43, v43 quad_perm:[2,3,0,1] row_mask:0xf bank_mask:0xf
	s_nop 1
	v_add_f32_dpp v43, v43, v43 row_half_mirror row_mask:0xf bank_mask:0xf
	s_nop 1
	v_add_f32_dpp v43, v43, v43 row_mirror row_mask:0xf bank_mask:0xf
	s_nop 1
	v_readlane_b32 vcc_lo, v43, 0
	v_readlane_b32 vcc_hi, v43, 16
	s_nop 1
	v_mov_b32_e32 v8, vcc_lo
	v_add_f32_e32 v8, vcc_hi, v8
	v_readlane_b32 vcc_lo, v43, 32
	v_readlane_b32 vcc_hi, v43, 48
	s_nop 1
	v_add_f32_e32 v8, vcc_lo, v8
	v_add_f32_e32 v43, vcc_hi, v8
	v_mov_b32_e32 v68, v43
	v_pk_fma_f32 v[52:53], v[68:69], v[40:41], v[52:53] op_sel_hi:[0,0,1]
	v_pk_fma_f32 v[54:55], v[68:69], v[40:41], v[54:55] op_sel_hi:[0,0,1]
	v_pk_fma_f32 v[56:57], v[68:69], v[40:41], v[56:57] op_sel_hi:[0,0,1]
	v_pk_fma_f32 v[58:59], v[68:69], v[40:41], v[58:59] op_sel_hi:[0,0,1]
	v_pk_fma_f32 v[60:61], v[68:69], v[40:41], v[60:61] op_sel_hi:[0,0,1]
	v_pk_fma_f32 v[62:63], v[68:69], v[40:41], v[62:63] op_sel_hi:[0,0,1]
	v_pk_fma_f32 v[64:65], v[68:69], v[40:41], v[64:65] op_sel_hi:[0,0,1]
	v_pk_fma_f32 v[66:67], v[68:69], v[40:41], v[66:67] op_sel_hi:[0,0,1]
	v_pk_mul_f32 v[68:69], v[52:53], v[52:53]
	v_pk_fma_f32 v[68:69], v[54:55], v[54:55], v[68:69]
	v_pk_fma_f32 v[68:69], v[56:57], v[56:57], v[68:69]
	v_pk_fma_f32 v[68:69], v[58:59], v[58:59], v[68:69]
	v_pk_fma_f32 v[68:69], v[60:61], v[60:61], v[68:69]
	v_pk_fma_f32 v[68:69], v[62:63], v[62:63], v[68:69]
	v_pk_fma_f32 v[68:69], v[64:65], v[64:65], v[68:69]
	v_pk_fma_f32 v[68:69], v[66:67], v[66:67], v[68:69]
	v_add_f32_e32 v43, v68, v69
	s_nop 1
	v_add_f32_dpp v43, v43, v43 quad_perm:[1,0,3,2] row_mask:0xf bank_mask:0xf
	s_nop 1
	v_add_f32_dpp v43, v43, v43 quad_perm:[2,3,0,1] row_mask:0xf bank_mask:0xf
	s_nop 1
	v_add_f32_dpp v43, v43, v43 row_half_mirror row_mask:0xf bank_mask:0xf
	s_nop 1
	v_add_f32_dpp v43, v43, v43 row_mirror row_mask:0xf bank_mask:0xf
	s_nop 1
	v_readlane_b32 vcc_lo, v43, 0
	v_readlane_b32 vcc_hi, v43, 16
	s_nop 1
	v_mov_b32_e32 v8, vcc_lo
	v_add_f32_e32 v8, vcc_hi, v8
	v_readlane_b32 vcc_lo, v43, 32
	v_readlane_b32 vcc_hi, v43, 48
	s_nop 1
	v_add_f32_e32 v8, vcc_lo, v8
	v_add_f32_e32 v43, vcc_hi, v8
	v_fmamk_f32 v43, v43, 0x3a800000, v248
	v_cmp_gt_f32_e32 vcc, s96, v43
	v_mul_f32_e32 v8, 0x4b800000, v43
	s_nop 0
	v_cndmask_b32_e32 v43, v43, v8, vcc
	v_rsq_f32_e32 v43, v43
	s_nop 0
	v_mul_f32_e32 v8, 0x45800000, v43
	v_cndmask_b32_e32 v68, v43, v8, vcc
	v_pk_mul_f32 v[52:53], v[52:53], v[68:69] op_sel_hi:[1,0]
	v_pk_mul_f32 v[54:55], v[54:55], v[68:69] op_sel_hi:[1,0]
	v_pk_mul_f32 v[56:57], v[56:57], v[68:69] op_sel_hi:[1,0]
	v_pk_mul_f32 v[58:59], v[58:59], v[68:69] op_sel_hi:[1,0]
	v_pk_mul_f32 v[60:61], v[60:61], v[68:69] op_sel_hi:[1,0]
	v_pk_mul_f32 v[62:63], v[62:63], v[68:69] op_sel_hi:[1,0]
	v_pk_mul_f32 v[64:65], v[64:65], v[68:69] op_sel_hi:[1,0]
	v_pk_mul_f32 v[66:67], v[66:67], v[68:69] op_sel_hi:[1,0]
	v_pk_fma_f32 v[52:53], v[4:5], v[52:53], v[14:15]
	v_pk_fma_f32 v[54:55], v[6:7], v[54:55], v[16:17]
	v_pk_fma_f32 v[56:57], v[0:1], v[56:57], v[10:11]
	v_pk_fma_f32 v[58:59], v[2:3], v[58:59], v[12:13]
	v_pk_fma_f32 v[60:61], v[22:23], v[60:61], v[30:31]
	v_pk_fma_f32 v[62:63], v[24:25], v[62:63], v[32:33]
	v_pk_fma_f32 v[64:65], v[18:19], v[64:65], v[26:27]
	v_pk_fma_f32 v[66:67], v[20:21], v[66:67], v[28:29]
	s_and_b64 vcc, exec, s[6:7]
	s_cbranch_vccz .Lln2r_f32_1
	v_cvt_pk_bf16_f32 v52, v52, v53
	v_cvt_pk_bf16_f32 v53, v54, v55
	v_cvt_pk_bf16_f32 v54, v56, v57
	v_cvt_pk_bf16_f32 v55, v58, v59
	v_cvt_pk_bf16_f32 v56, v60, v61
	v_cvt_pk_bf16_f32 v57, v62, v63
	v_cvt_pk_bf16_f32 v58, v64, v65
	v_cvt_pk_bf16_f32 v59, v66, v67
	global_store_dwordx4 v[44:45], v[52:55], off offset:-1024
	global_store_dwordx4 v[44:45], v[56:59], off
	s_waitcnt vmcnt(4)
	s_branch .Lln2r_latch_1

; __device__ __forceinline__ unsigned cvt_pk_bf16(float lo, float hi) { const f32x2c v = {lo, hi}; const bf16x2c b = __builtin_convertvector(v, bf16x2c); return __builtin_bit_cast(unsigned, b); }
; __device__ __forceinline__ float bflo(unsigned u) { return __uint_as_float(u << 16); }
; __device__ __forceinline__ float bfhi(unsigned u) { return __uint_as_float(u & 0xffff0000u); }
; __device__ void phase_ln(KP p, const float* g, const float* b, bool final_out, int tid_in, int r0, int r1, int b0) {
;     ...
;     for (int row = r0 + gw; row < r1; row += nw) {
;         bf16_t* xr = Xb + (size_t)row * 1024 + lane * 8;
;         f32x4 x[4]; float s = 0.f;
; #pragma unroll
;         for (int j = 0; j < 2; ++j) { const u32x4v u = *(const u32x4v*)(xr + 512 * j);
;             x[2 * j] = (f32x4){bflo(u[0]), bfhi(u[0]), bflo(u[1]), bfhi(u[1])}; x[2 * j + 1] = (f32x4){bflo(u[2]), bfhi(u[2]), bflo(u[3]), bfhi(u[3])}; }
; #pragma unroll
;         for (int j = 0; j < 4; ++j) s += x[j][0] + x[j][1] + x[j][2] + x[j][3];
;         const float mu = wave_sum(s, lane) * (1.f / 1024.f); float v = 0.f;
; #pragma unroll
;         for (int j = 0; j < 4; ++j) { x[j] = x[j] - mu; v += x[j][0] * x[j][0] + x[j][1] * x[j][1] + x[j][2] * x[j][2] + x[j][3] * x[j][3]; }
;         const float r = rsqrtf(wave_sum(v, lane) * (1.f / 1024.f) + LN_EPS);
; #pragma unroll
;         for (int j = 0; j < 2; ++j) {
;             const f32x4 y0 = x[2 * j] * r * gv[2 * j] + bv[2 * j], y1 = x[2 * j + 1] * r * gv[2 * j + 1] + bv[2 * j + 1];
;             if (final_out) { float* yo = p->out + (size_t)row * 1024 + lane * 8 + 512 * j; __builtin_nontemporal_store(y0, (f32x4*)yo); __builtin_nontemporal_store(y1, (f32x4*)(yo + 4)); }
;             else { u32x4v o; o[0] = cvt_pk_bf16(y0[0], y0[1]); o[1] = cvt_pk_bf16(y0[2], y0[3]); o[2] = cvt_pk_bf16(y1[0], y1[1]); o[3] = cvt_pk_bf16(y1[2], y1[3]);
;                 *(u32x4v*)(xr + 512 * j) = o; }
.Lln2r_b2:
	v_lshlrev_b32_e32 v52, 16, v86
	v_and_b32_e32 v53, 0xffff0000, v86
	v_lshlrev_b32_e32 v54, 16, v87
	v_and_b32_e32 v55, 0xffff0000, v87
	v_lshlrev_b32_e32 v56, 16, v88
	v_and_b32_e32 v57, 0xffff0000, v88
	v_lshlrev_b32_e32 v58, 16, v89
	v_and_b32_e32 v59, 0xffff0000, v89
	v_lshlrev_b32_e32 v60, 16, v90
	v_and_b32_e32 v61, 0xffff0000, v90
	v_lshlrev_b32_e32 v62, 16, v91
	v_and_b32_e32 v63, 0xffff0000, v91
	v_lshlrev_b32_e32 v64, 16, v92
	v_and_b32_e32 v65, 0xffff0000, v92
	v_lshlrev_b32_e32 v66, 16, v93
	v_and_b32_e32 v67, 0xffff0000, v93
	global_load_dwordx4 v[78:81], v[94:95], off offset:-1024
	global_load_dwordx4 v[82:85], v[94:95], off
	v_lshl_add_u64 v[94:95], v[94:95], 0, s[34:35]
	v_pk_add_f32 v[68:69], v[52:53], v[54:55]
	v_pk_add_f32 v[68:69], v[68:69], v[56:57]
	v_pk_add_f32 v[68:69], v[68:69], v[58:59]
	v_pk_add_f32 v[68:69], v[68:69], v[60:61]
	v_pk_add_f32 v[68:69], v[68:69], v[62:63]
	v_pk_add_f32 v[68:69], v[68:69], v[64:65]
	v_pk_add_f32 v[68:69], v[68:69], v[66:67]
	v_add_f32_e32 v43, v68, v69
	s_nop 1
	v_add_f32_dpp v43, v43, v43 quad_perm:[1,0,3,2] row_mask:0xf bank_mask:0xf
	s_nop 1
	v_add_f32_dpp v43, v43, v43 quad_perm:[2,3,0,1] row_mask:0xf bank_mask:0xf
	s_nop 1
	v_add_f32_dpp v43, v43, v43 row_half_mirror row_mask:0xf bank_mask:0xf
	s_nop 1
	v_add_f32_dpp v43, v43, v43 row_mirror row_mask:0xf bank_mask:0xf
	s_nop 1
	v_readlane_b32 vcc_lo, v43, 0
	v_readlane_b32 vcc_hi, v43, 16
	s_nop 1
	v_mov_b32_e32 v8, vcc_lo
	v_add_f32_e32 v8, vcc_hi, v8
	v_readlane_b32 vcc_lo, v43, 32
	v_readlane_b32 vcc_hi, v43, 48
	s_nop 1
	v_add_f32_e32 v8, vcc_lo, v8
	v_add_f32_e32 v43, vcc_hi, v8
	v_mov_b32_e32 v68, v43
	v_pk_fma_f32 v[52:53], v[68:69], v[40:41], v[52:53] op_sel_hi:[0,0,1]
	v_pk_fma_f32 v[54:55], v[68:69], v[40:41], v[54:55] op_sel_hi:[0,0,1]
	v_pk_fma_f32 v[56:57], v[68:69], v[40:41], v[56:57] op_sel_hi:[0,0,1]
	v_pk_fma_f32 v[58:59], v[68:69], v[40:41], v[58:59] op_sel_hi:[0,0,1]
	v_pk_fma_f32 v[60:61], v[68:69], v[40:41], v[60:61] op_sel_hi:[0,0,1]
	v_pk_fma_f32 v[62:63], v[68:69], v[40:41], v[62:63] op_sel_hi:[0,0,1]
	v_pk_fma_f32 v[64:65], v[68:69], v[40:41], v[64:65] op_sel_hi:[0,0,1]
	v_pk_fma_f32 v[66:67], v[68:69], v[40:41], v[66:67] op_sel_hi:[0,0,1]
	v_pk_mul_f32 v[68:69], v[52:53], v[52:53]
	v_pk_fma_f32 v[68:69], v[54:55], v[54:55], v[68:69]
	v_pk_fma_f32 v[68:69], v[56:57], v[56:57], v[68:69]
	v_pk_fma_f32 v[68:69], v[58:59], v[58:59], v[68:69]
	v_pk_fma_f32 v[68:69], v[60:61], v[60:61], v[68:69]
	v_pk_fma_f32 v[68:69], v[62:63], v[62:63], v[68:69]
	v_pk_fma_f32 v[68:69], v[64:65], v[64:65], v[68:69]
	v_pk_fma_f32 v[68:69], v[66:67], v[66:67], v[68:69]
	v_add_f32_e32 v43, v68, v69
	s_nop 1
	v_add_f32_dpp v43, v43, v43 quad_perm:[1,0,3,2] row_mask:0xf bank_mask:0xf
	s_nop 1
	v_add_f32_dpp v43, v43, v43 quad_perm:[2,3,0,1] row_mask:0xf bank_mask:0xf
	s_nop 1
	v_add_f32_dpp v43, v43, v43 row_half_mirror row_mask:0xf bank_mask:0xf
	s_nop 1
	v_add_f32_dpp v43, v43, v43 row_mirror row_mask:0xf bank_mask:0xf
	s_nop 1
	v_readlane_b32 vcc_lo, v43, 0
	v_readlane_b32 vcc_hi, v43, 16
	s_nop 1
	v_mov_b32_e32 v8, vcc_lo
	v_add_f32_e32 v8, vcc_hi, v8
	v_readlane_b32 vcc_lo, v43, 32
	v_readlane_b32 vcc_hi, v43, 48
	s_nop 1
	v_add_f32_e32 v8, vcc_lo, v8
	v_add_f32_e32 v43, vcc_hi, v8
	v_fmamk_f32 v43, v43, 0x3a800000, v248
	v_cmp_gt_f32_e32 vcc, s96, v43
	v_mul_f32_e32 v8, 0x4b800000, v43
	s_nop 0
	v_cndmask_b32_e32 v43, v43, v8, vcc
	v_rsq_f32_e32 v43, v43
	s_nop 0
	v_mul_f32_e32 v8, 0x45800000, v43
	v_cndmask_b32_e32 v68, v43, v8, vcc
	v_pk_mul_f32 v[52:53], v[52:53], v[68:69] op_sel_hi:[1,0]
	v_pk_mul_f32 v[54:55], v[54:55], v[68:69] op_sel_hi:[1,0]
	v_pk_mul_f32 v[56:57], v[56:57], v[68:69] op_sel_hi:[1,0]
	v_pk_mul_f32 v[58:59], v[58:59], v[68:69] op_sel_hi:[1,0]
	v_pk_mul_f32 v[60:61], v[60:61], v[68:69] op_sel_hi:[1,0]
	v_pk_mul_f32 v[62:63], v[62:63], v[68:69] op_sel_hi:[1,0]
	v_pk_mul_f32 v[64:65], v[64:65], v[68:69] op_sel_hi:[1,0]
	v_pk_mul_f32 v[66:67], v[66:67], v[68:69] op_sel_hi:[1,0]
	v_pk_fma_f32 v[52:53], v[4:5], v[52:53], v[14:15]
	v_pk_fma_f32 v[54:55], v[6:7], v[54:55], v[16:17]
	v_pk_fma_f32 v[56:57], v[0:1], v[56:57], v[10:11]
	v_pk_fma_f32 v[58:59], v[2:3], v[58:59], v[12:13]
	v_pk_fma_f32 v[60:61], v[22:23], v[60:61], v[30:31]
	v_pk_fma_f32 v[62:63], v[24:25], v[62:63], v[32:33]
	v_pk_fma_f32 v[64:65], v[18:19], v[64:65], v[26:27]
	v_pk_fma_f32 v[66:67], v[20:21], v[66:67], v[28:29]
	s_and_b64 vcc, exec, s[6:7]
	s_cbranch_vccz .Lln2r_f32_2
	v_cvt_pk_bf16_f32 v52, v52, v53
	v_cvt_pk_bf16_f32 v53, v54, v55
	v_cvt_pk_bf16_f32 v54, v56, v57
	v_cvt_pk_bf16_f32 v55, v58, v59
	v_cvt_pk_bf16_f32 v56, v60, v61
	v_cvt_pk_bf16_f32 v57, v62, v63
	v_cvt_pk_bf16_f32 v58, v64, v65
	v_cvt_pk_bf16_f32 v59, v66, v67
	global_store_dwordx4 v[44:45], v[52:55], off offset:-1024
	global_store_dwordx4 v[44:45], v[56:59], off
	s_waitcnt vmcnt(4)
	s_branch .Lln2r_latch_2

; __device__ __forceinline__ unsigned cvt_pk_bf16(float lo, float hi) { const f32x2c v = {lo, hi}; const bf16x2c b = __builtin_convertvector(v, bf16x2c); return __builtin_bit_cast(unsigned, b); }
; __device__ __forceinline__ float bflo(unsigned u) { return __uint_as_float(u << 16); }
; __device__ __forceinline__ float bfhi(unsigned u) { return __uint_as_float(u & 0xffff0000u); }
; __device__ void phase_ln(KP p, const float* g, const float* b, bool final_out, int tid_in, int r0, int r1, int b0) {
;     ...
;     for (int row = r0 + gw; row < r1; row += nw) {
;         bf16_t* xr = Xb + (size_t)row * 1024 + lane * 8;
;         f32x4 x[4]; float s = 0.f;
; #pragma unroll
;         for (int j = 0; j < 2; ++j) { const u32x4v u = *(const u32x4v*)(xr + 512 * j);
;             x[2 * j] = (f32x4){bflo(u[0]), bfhi(u[0]), bflo(u[1]), bfhi(u[1])}; x[2 * j + 1] = (f32x4){bflo(u[2]), bfhi(u[2]), bflo(u[3]), bfhi(u[3])}; }
; #pragma unroll
;         for (int j = 0; j < 4; ++j) s += x[j][0] + x[j][1] + x[j][2] + x[j][3];
;         const float mu = wave_sum(s, lane) * (1.f / 1024.f); float v = 0.f;
; #pragma unroll
;         for (int j = 0; j < 4; ++j) { x[j] = x[j] - mu; v += x[j][0] * x[j][0] + x[j][1] * x[j][1] + x[j][2] * x[j][2] + x[j][3] * x[j][3]; }
;         const float r = rsqrtf(wave_sum(v, lane) * (1.f / 1024.f) + LN_EPS);
; #pragma unroll
;         for (int j = 0; j < 2; ++j) {
;             const f32x4 y0 = x[2 * j] * r * gv[2 * j] + bv[2 * j], y1 = x[2 * j + 1] * r * gv[2 * j + 1] + bv[2 * j + 1];
;             if (final_out) { float* yo = p->out + (size_t)row * 1024 + lane * 8 + 512 * j; __builtin_nontemporal_store(y0, (f32x4*)yo); __builtin_nontemporal_store(y1, (f32x4*)(yo + 4)); }
;             else { u32x4v o; o[0] = cvt_pk_bf16(y0[0], y0[1]); o[1] = cvt_pk_bf16(y0[2], y0[3]); o[2] = cvt_pk_bf16(y1[0], y1[1]); o[3] = cvt_pk_bf16(y1[2], y1[3]);
;                 *(u32x4v*)(xr + 512 * j) = o; }
;         }
;     }
.Lln2r_latch_2:
	v_add_u32_e32 v42, s30, v42
	v_cmp_le_i32_e32 vcc, s0, v42
	v_lshl_add_u64 v[44:45], v[44:45], 0, s[34:35]
	s_or_b64 s[48:49], vcc, s[48:49]
	v_lshl_add_u64 v[46:47], v[46:47], 0, s[42:43]
	s_andn2_b64 exec, exec, s[48:49]
	s_cbranch_execnz .Lln2r_b0
.Lln2r_exit:
	s_waitcnt vmcnt(0)
.LBB0_997:
	s_or_b64 exec, exec, s[16:17]
